# w24+sigfix + weight-copy publication counted on 16 sharded counters, checked with the group arrival before phase 5
# speedup vs baseline: 1.0055x; 1.0055x over previous
; #define GSYNC() do { xcd_barrier(xbar); xcd_barrier(xbar); } while (0)
; #define GSYNC() xcd_barrier(xbar)
; #define REP(p) for (int rep_ = 0; rep_ < (((PROBE_MASK >> (p)) & 1) ? 2 : 1); ++rep_)
; __global__ void __launch_bounds__(NTHR, 2) fwd_megakernel(Args args) {
;     ...
;     weight_copy_items(args, lds, 16 * 96 + 32, 16 * 96 + 32 + 16 * 32 + 16 * 129 + 16 * 32, G);
;     GSYNC(); }
;     REP(4) { hgrn_scan_phase((const float*)(ws + WS_LST), (const float*)(ws + WS_DTOT), (float*)(ws + WS_SST), G);
.LBB0_346:
	s_or_b64 exec, exec, s[0:1]
	s_waitcnt vmcnt(0)
	s_barrier
	s_and_saveexec_b64 s[100:101], s[92:93]
	s_cbranch_execz .Lp4_polled
	v_mov_b32_e32 v250, 0
	s_and_b32 s98, s91, 15
	s_lshl_b32 s98, s98, 6
	s_add_i32 s98, s98, 0x2000
	v_mov_b32_e32 v252, s98
	v_mov_b32_e32 v251, 1
	global_atomic_add v252, v251, s[10:11]

; #define GSYNC() do { xcd_barrier(xbar); xcd_barrier(xbar); } while (0)
; #define GSYNC() xcd_barrier(xbar)
; #define REP(p) for (int rep_ = 0; rep_ < (((PROBE_MASK >> (p)) & 1) ? 2 : 1); ++rep_)
; __global__ void __launch_bounds__(NTHR, 2) fwd_megakernel(Args args) {
;     ...
;     REP(4) { hgrn_scan_phase((const float*)(ws + WS_LST), (const float*)(ws + WS_DTOT), (float*)(ws + WS_SST), G);
;     GSYNC(); }
;     REP(5) { for (int u = blockIdx.x; u < 256; u += G) hgrn_unit<true>(lds, u, P0, args.in[5], args.in[7], nullptr, (const float*)(ws + WS_SST), nullptr, MIX);
;     bias1_phase((const bf16*)(ws + WS_W1IN), mod + 2 * 3072, (float*)(ws + WS_BIAS1), G);
.LBB0_403:
	s_or_b64 exec, exec, s[0:1]
	s_waitcnt vmcnt(0)
	s_barrier
	s_cmp_eq_u32 s6, 0x100
	s_cbranch_scc0 .Lg5_orig
	s_and_saveexec_b64 s[0:1], s[92:93]
	s_cbranch_execz .Lg5_done
	v_readlane_b32 s98, v249, 2
	s_lshr_b32 s98, s98, 5
	s_lshl_b32 s98, s98, 8
	s_add_i32 s98, s98, 0x1000
	s_mov_b64 exec, 0xffff
	v_mov_b32_e32 v250, s98
	v_mov_b32_e32 v251, 1
	v_lshlrev_b32_e32 v252, 6, v208
	v_add_u32_e32 v252, 0x2000, v252
	s_mov_b64 exec, 1
	global_atomic_add v250, v251, s[10:11]
	s_mov_b64 exec, 0xffff
.Lg5_poll:
	global_load_dword v251, v250, s[10:11] sc1
	global_load_dword v253, v252, s[10:11] sc1
	s_waitcnt vmcnt(0)
	v_cmp_gt_u32_e32 vcc, 32, v251
	s_nop 3
	s_cmp_eq_u64 vcc, 0
	s_cbranch_scc0 .Lg5_again
	v_cmp_gt_u32_e32 vcc, 16, v253
	s_nop 3
	s_cmp_eq_u64 vcc, 0
	s_cbranch_scc1 .Lg5_pollend
